# speedup vs baseline: 1.0005x; 1.0005x over previous
;     __device__ __forceinline__ void operator()(const f32x4 (&acc)[2][2][4][2], const Unit& u, int wr, int wc, int fr, int fq) const {
;     ...
;         if (gain) {
; #pragma unroll
;             for (int bj = 0; bj < 2; ++bj)
; #pragma unroll
;                 for (int n = 0; n < 2; ++n) gv[bj][n] = *(const f32x4*)(gain + col0 + bj * HALF + n * 16);
;         }
; #pragma unroll
;         for (int aim = 0; aim < 4; ++aim) { const int ai = aim >> 1;
.LBB0_605:
	s_andn2_b64 vcc, exec, s[0:1]
	s_cbranch_vccnz .LBB0_650
	s_and_b64 vcc, exec, s[74:75]
	s_cbranch_vccnz .Lepi1_fast
	s_branch .Lepi1_nogain
	v_lshl_or_b32 v206, s63, 8, v233
	v_cndmask_b32_e64 v0, 0, 1, s[74:75]
	v_cmp_ne_u32_e64 s[44:45], 1, v0
	s_andn2_b64 vcc, exec, s[74:75]
	v_ashrrev_i32_e32 v207, 31, v206
	s_cbranch_vccnz .LBB0_608
	v_lshl_add_u64 v[130:131], v[206:207], 2, s[20:21]
	global_load_dwordx4 v[142:145], v[130:131], off
	global_load_dwordx4 v[138:141], v[130:131], off offset:64
	global_load_dwordx4 v[134:137], v[130:131], off offset:512
	s_nop 0
	global_load_dwordx4 v[130:133], v[130:131], off offset:576

;     __device__ __forceinline__ void operator()(const f32x4 (&acc)[2][2][4][2], const Unit& u, int wr, int wc, int fr, int fq) const {
;     ...
;         for (int aim = 0; aim < 4; ++aim) { const int ai = aim >> 1;
;             f32x4 res[4][2][2];
; #pragma unroll
;             for (int m = (aim & 1) * 2; m < (aim & 1) * 2 + 2; ++m)
; #pragma unroll
;                 for (int bj = 0; bj < 2; ++bj)
; #pragma unroll
;                     for (int n = 0; n < 2; ++n) res[m][bj][n] = *(const f32x4*)(C + (size_t)(row0 + ai * HALF + m * 16) * ldc + col0 + bj * HALF + n * 16);
; #pragma unroll
;             for (int m = (aim & 1) * 2; m < (aim & 1) * 2 + 2; ++m) { const int row = row0 + ai * HALF + m * 16; float* rowp = C + (size_t)row * ldc + col0; float sq = 0.f;
; #pragma unroll
;                 for (int bj = 0; bj < 2; ++bj)
; #pragma unroll
;                     for (int n = 0; n < 2; ++n) { f32x4* p = (f32x4*)(rowp + bj * HALF + n * 16); const f32x4 x = res[m][bj][n] + acc[ai][bj][m][n] * scale; *p = x;
.Lepi1_nogain:
	v_lshl_or_b32 v206, s63, 8, v233
	v_add_u32_e32 v0, s48, v235
	v_lshlrev_b32_e32 v178, 13, v0
	v_lshl_add_u32 v178, v206, 2, v178
	s_add_u32 s0, s4, 0x0
	s_addc_u32 s1, s5, 0
	global_load_dwordx4 v[146:149], v178, s[0:1] offset:0
	global_load_dwordx4 v[150:153], v178, s[0:1] offset:64
	global_load_dwordx4 v[154:157], v178, s[0:1] offset:512
	global_load_dwordx4 v[158:161], v178, s[0:1] offset:576
	s_add_u32 s0, s4, 0x20000
	s_addc_u32 s1, s5, 0
	global_load_dwordx4 v[162:165], v178, s[0:1] offset:0
	global_load_dwordx4 v[166:169], v178, s[0:1] offset:64
	global_load_dwordx4 v[170:173], v178, s[0:1] offset:512
	global_load_dwordx4 v[174:177], v178, s[0:1] offset:576
	s_add_u32 s0, s4, 0x40000
	s_addc_u32 s1, s5, 0
	global_load_dwordx4 v[206:209], v178, s[0:1] offset:0
	global_load_dwordx4 v[210:213], v178, s[0:1] offset:64
	global_load_dwordx4 v[214:217], v178, s[0:1] offset:512
	global_load_dwordx4 v[218:221], v178, s[0:1] offset:576
	s_waitcnt vmcnt(8)
	v_pk_fma_f32 v[126:127], s[22:23], v[126:127], v[146:147]
	v_pk_fma_f32 v[128:129], s[22:23], v[128:129], v[148:149]
	v_pk_fma_f32 v[122:123], s[22:23], v[122:123], v[150:151]
	v_pk_fma_f32 v[124:125], s[22:23], v[124:125], v[152:153]
	v_pk_fma_f32 v[94:95], s[22:23], v[94:95], v[154:155]
	v_pk_fma_f32 v[96:97], s[22:23], v[96:97], v[156:157]
	v_pk_fma_f32 v[90:91], s[22:23], v[90:91], v[158:159]
	v_pk_fma_f32 v[92:93], s[22:23], v[92:93], v[160:161]
	s_add_u32 s0, s4, 0x60000
	s_addc_u32 s1, s5, 0
	global_load_dwordx4 v[146:149], v178, s[0:1] offset:0
	global_load_dwordx4 v[150:153], v178, s[0:1] offset:64
	global_load_dwordx4 v[154:157], v178, s[0:1] offset:512
	global_load_dwordx4 v[158:161], v178, s[0:1] offset:576
	s_add_u32 s0, s4, 0x0
	s_addc_u32 s1, s5, 0
	global_store_dwordx4 v178, v[126:129], s[0:1] offset:0
	global_store_dwordx4 v178, v[122:125], s[0:1] offset:64
	global_store_dwordx4 v178, v[94:97], s[0:1] offset:512
	global_store_dwordx4 v178, v[90:93], s[0:1] offset:576
	s_waitcnt vmcnt(12)
	v_pk_fma_f32 v[118:119], s[22:23], v[118:119], v[162:163]
	v_pk_fma_f32 v[120:121], s[22:23], v[120:121], v[164:165]
	v_pk_fma_f32 v[114:115], s[22:23], v[114:115], v[166:167]
	v_pk_fma_f32 v[116:117], s[22:23], v[116:117], v[168:169]
	v_pk_fma_f32 v[86:87], s[22:23], v[86:87], v[170:171]
	v_pk_fma_f32 v[88:89], s[22:23], v[88:89], v[172:173]
	v_pk_fma_f32 v[82:83], s[22:23], v[82:83], v[174:175]
	v_pk_fma_f32 v[84:85], s[22:23], v[84:85], v[176:177]
	s_add_u32 s0, s4, 0x100000
	s_addc_u32 s1, s5, 0
	global_load_dwordx4 v[162:165], v178, s[0:1] offset:0
	global_load_dwordx4 v[166:169], v178, s[0:1] offset:64
	global_load_dwordx4 v[170:173], v178, s[0:1] offset:512
	global_load_dwordx4 v[174:177], v178, s[0:1] offset:576
	s_add_u32 s0, s4, 0x20000
	s_addc_u32 s1, s5, 0
	global_store_dwordx4 v178, v[118:121], s[0:1] offset:0
	global_store_dwordx4 v178, v[114:117], s[0:1] offset:64
	global_store_dwordx4 v178, v[86:89], s[0:1] offset:512
	global_store_dwordx4 v178, v[82:85], s[0:1] offset:576
	s_waitcnt vmcnt(16)
	v_pk_fma_f32 v[110:111], s[22:23], v[110:111], v[206:207]
	v_pk_fma_f32 v[112:113], s[22:23], v[112:113], v[208:209]
	v_pk_fma_f32 v[106:107], s[22:23], v[106:107], v[210:211]
	v_pk_fma_f32 v[108:109], s[22:23], v[108:109], v[212:213]
	v_pk_fma_f32 v[78:79], s[22:23], v[78:79], v[214:215]
	v_pk_fma_f32 v[80:81], s[22:23], v[80:81], v[216:217]
	v_pk_fma_f32 v[74:75], s[22:23], v[74:75], v[218:219]
	v_pk_fma_f32 v[76:77], s[22:23], v[76:77], v[220:221]
	s_add_u32 s0, s4, 0x120000
	s_addc_u32 s1, s5, 0
	global_load_dwordx4 v[206:209], v178, s[0:1] offset:0
	global_load_dwordx4 v[210:213], v178, s[0:1] offset:64
	global_load_dwordx4 v[214:217], v178, s[0:1] offset:512
	global_load_dwordx4 v[218:221], v178, s[0:1] offset:576
	s_add_u32 s0, s4, 0x40000
	s_addc_u32 s1, s5, 0
	global_store_dwordx4 v178, v[110:113], s[0:1] offset:0
	global_store_dwordx4 v178, v[106:109], s[0:1] offset:64
	global_store_dwordx4 v178, v[78:81], s[0:1] offset:512
	global_store_dwordx4 v178, v[74:77], s[0:1] offset:576
	s_waitcnt vmcnt(20)
;     __device__ __forceinline__ void operator()(const f32x4 (&acc)[2][2][4][2], const Unit& u, int wr, int wc, int fr, int fq) const {
;     ...
;         for (int aim = 0; aim < 4; ++aim) { const int ai = aim >> 1;
;             f32x4 res[4][2][2];
; #pragma unroll
;             for (int m = (aim & 1) * 2; m < (aim & 1) * 2 + 2; ++m)
; #pragma unroll
;                 for (int bj = 0; bj < 2; ++bj)
; #pragma unroll
;                     for (int n = 0; n < 2; ++n) res[m][bj][n] = *(const f32x4*)(C + (size_t)(row0 + ai * HALF + m * 16) * ldc + col0 + bj * HALF + n * 16);
; #pragma unroll
;             for (int m = (aim & 1) * 2; m < (aim & 1) * 2 + 2; ++m) { const int row = row0 + ai * HALF + m * 16; float* rowp = C + (size_t)row * ldc + col0; float sq = 0.f;
; #pragma unroll
;                 for (int bj = 0; bj < 2; ++bj)
; #pragma unroll
;                     for (int n = 0; n < 2; ++n) { f32x4* p = (f32x4*)(rowp + bj * HALF + n * 16); const f32x4 x = res[m][bj][n] + acc[ai][bj][m][n] * scale; *p = x;
	v_pk_fma_f32 v[102:103], s[22:23], v[102:103], v[146:147]
	v_pk_fma_f32 v[104:105], s[22:23], v[104:105], v[148:149]
	v_pk_fma_f32 v[98:99], s[22:23], v[98:99], v[150:151]
	v_pk_fma_f32 v[100:101], s[22:23], v[100:101], v[152:153]
	v_pk_fma_f32 v[70:71], s[22:23], v[70:71], v[154:155]
	v_pk_fma_f32 v[72:73], s[22:23], v[72:73], v[156:157]
	v_pk_fma_f32 v[66:67], s[22:23], v[66:67], v[158:159]
	v_pk_fma_f32 v[68:69], s[22:23], v[68:69], v[160:161]
	s_add_u32 s0, s4, 0x140000
	s_addc_u32 s1, s5, 0
	global_load_dwordx4 v[146:149], v178, s[0:1] offset:0
	global_load_dwordx4 v[150:153], v178, s[0:1] offset:64
	global_load_dwordx4 v[154:157], v178, s[0:1] offset:512
	global_load_dwordx4 v[158:161], v178, s[0:1] offset:576
	s_add_u32 s0, s4, 0x60000
	s_addc_u32 s1, s5, 0
	global_store_dwordx4 v178, v[102:105], s[0:1] offset:0
	global_store_dwordx4 v178, v[98:101], s[0:1] offset:64
	global_store_dwordx4 v178, v[70:73], s[0:1] offset:512
	global_store_dwordx4 v178, v[66:69], s[0:1] offset:576
	s_waitcnt vmcnt(20)
	v_pk_fma_f32 v[62:63], s[22:23], v[62:63], v[162:163]
	v_pk_fma_f32 v[64:65], s[22:23], v[64:65], v[164:165]
	v_pk_fma_f32 v[58:59], s[22:23], v[58:59], v[166:167]
	v_pk_fma_f32 v[60:61], s[22:23], v[60:61], v[168:169]
	v_pk_fma_f32 v[30:31], s[22:23], v[30:31], v[170:171]
	v_pk_fma_f32 v[32:33], s[22:23], v[32:33], v[172:173]
	v_pk_fma_f32 v[26:27], s[22:23], v[26:27], v[174:175]
	v_pk_fma_f32 v[28:29], s[22:23], v[28:29], v[176:177]
	s_add_u32 s0, s4, 0x160000
	s_addc_u32 s1, s5, 0
	global_load_dwordx4 v[162:165], v178, s[0:1] offset:0
	global_load_dwordx4 v[166:169], v178, s[0:1] offset:64
	global_load_dwordx4 v[170:173], v178, s[0:1] offset:512
	global_load_dwordx4 v[174:177], v178, s[0:1] offset:576
	s_add_u32 s0, s4, 0x100000
	s_addc_u32 s1, s5, 0
	global_store_dwordx4 v178, v[62:65], s[0:1] offset:0
	global_store_dwordx4 v178, v[58:61], s[0:1] offset:64
	global_store_dwordx4 v178, v[30:33], s[0:1] offset:512
	global_store_dwordx4 v178, v[26:29], s[0:1] offset:576
	s_waitcnt vmcnt(20)
	v_pk_fma_f32 v[54:55], s[22:23], v[54:55], v[206:207]
	v_pk_fma_f32 v[56:57], s[22:23], v[56:57], v[208:209]
	v_pk_fma_f32 v[50:51], s[22:23], v[50:51], v[210:211]
	v_pk_fma_f32 v[52:53], s[22:23], v[52:53], v[212:213]
	v_pk_fma_f32 v[22:23], s[22:23], v[22:23], v[214:215]
	v_pk_fma_f32 v[24:25], s[22:23], v[24:25], v[216:217]
	v_pk_fma_f32 v[18:19], s[22:23], v[18:19], v[218:219]
	v_pk_fma_f32 v[20:21], s[22:23], v[20:21], v[220:221]
	s_add_u32 s0, s4, 0x120000
	s_addc_u32 s1, s5, 0
	global_store_dwordx4 v178, v[54:57], s[0:1] offset:0
	global_store_dwordx4 v178, v[50:53], s[0:1] offset:64
	global_store_dwordx4 v178, v[22:25], s[0:1] offset:512
	global_store_dwordx4 v178, v[18:21], s[0:1] offset:576
	s_waitcnt vmcnt(16)
	v_pk_fma_f32 v[46:47], s[22:23], v[46:47], v[146:147]
	v_pk_fma_f32 v[48:49], s[22:23], v[48:49], v[148:149]
	v_pk_fma_f32 v[42:43], s[22:23], v[42:43], v[150:151]
	v_pk_fma_f32 v[44:45], s[22:23], v[44:45], v[152:153]
	v_pk_fma_f32 v[14:15], s[22:23], v[14:15], v[154:155]
	v_pk_fma_f32 v[16:17], s[22:23], v[16:17], v[156:157]
	v_pk_fma_f32 v[10:11], s[22:23], v[10:11], v[158:159]
	v_pk_fma_f32 v[12:13], s[22:23], v[12:13], v[160:161]
	s_add_u32 s0, s4, 0x140000
	s_addc_u32 s1, s5, 0
	global_store_dwordx4 v178, v[46:49], s[0:1] offset:0
	global_store_dwordx4 v178, v[42:45], s[0:1] offset:64
	global_store_dwordx4 v178, v[14:17], s[0:1] offset:512
	global_store_dwordx4 v178, v[10:13], s[0:1] offset:576
	s_waitcnt vmcnt(12)
	v_pk_fma_f32 v[38:39], s[22:23], v[38:39], v[162:163]
	v_pk_fma_f32 v[40:41], s[22:23], v[40:41], v[164:165]
	v_pk_fma_f32 v[34:35], s[22:23], v[34:35], v[166:167]
	v_pk_fma_f32 v[36:37], s[22:23], v[36:37], v[168:169]
	v_pk_fma_f32 v[6:7], s[22:23], v[6:7], v[170:171]
	v_pk_fma_f32 v[8:9], s[22:23], v[8:9], v[172:173]
	v_pk_fma_f32 v[2:3], s[22:23], v[2:3], v[174:175]
	v_pk_fma_f32 v[4:5], s[22:23], v[4:5], v[176:177]
	s_add_u32 s0, s4, 0x160000
	s_addc_u32 s1, s5, 0
	global_store_dwordx4 v178, v[38:41], s[0:1] offset:0
	global_store_dwordx4 v178, v[34:37], s[0:1] offset:64
	global_store_dwordx4 v178, v[6:9], s[0:1] offset:512
	global_store_dwordx4 v178, v[2:5], s[0:1] offset:576
	s_branch .LBB0_650
